# first K-iteration after an epilogue: first two counted waits relaxed to vmcnt(16) so the epilogue stores drain under the first MMA segments
# speedup vs baseline: 1.0119x; 1.0023x over previous
; #define PG8_STAGE(bufoff, gbase, voff) do { _Pragma("unroll") for (int _i = 0; _i < 2; ++_i) \
;         __builtin_amdgcn_global_load_lds((const unsigned*)((const char*)(gbase) + (voff)[_i]), (PG8_LAS unsigned*)(lds + (bufoff) + ldsw + _i * 8192), 16, 0, 0); } while (0)
; #define PG8_LDA(dst, b, h) do { _Pragma("unroll") for (int m = 0; m < 4; ++m) _Pragma("unroll") for (int k = 0; k < 2; ++k) dst[m][k] = *(const PG8_LAS bf16x8*)(lds + PG8_SA(b, h) + aoff + m * 2048 + k * 1024); } while (0)
; #define PG8_LDB(dst, b, h) do { _Pragma("unroll") for (int n = 0; n < 2; ++n) _Pragma("unroll") for (int k = 0; k < 2; ++k) dst[n][k] = *(const PG8_LAS bf16x8*)(lds + PG8_SB(b, h) + boff + n * 2048 + k * 1024); } while (0)
; #define PG8_MMA(ai, bj, At, Bt) do { __builtin_amdgcn_s_setprio(1); _Pragma("unroll") for (int m = 0; m < 4; ++m) _Pragma("unroll") for (int n = 0; n < 2; ++n) _Pragma("unroll") for (int k = 0; k < 2; ++k) \
;         acc[ai][bj][m][n] = __builtin_amdgcn_mfma_f32_16x16x32_bf16(Bt[n][k], At[m][k], acc[ai][bj][m][n], 0, 0, 0); __builtin_amdgcn_s_setprio(0); } while (0)
; #define PG8_WAIT_V(n) asm volatile("s_waitcnt vmcnt(" #n ")" ::: "memory")
; #define PG8_WAIT_L(n) asm volatile("s_waitcnt lgkmcnt(" #n ")" ::: "memory")
; #define PG8_BAR __builtin_amdgcn_s_barrier()
; #define PG8_SCHED __builtin_amdgcn_sched_barrier(0)
; template <class Epi, class Sched, bool ALIGN_EPI = false, bool SP2 = true>
; __device__ __forceinline__ void gemm_phase(PG8_LAS unsigned char* lds, const Gemm g, const Sched& S, const Epi& E, int wave_s) {
;     ...
;             PG8_LDB(B0, 0, 0); PG8_LDB(B1, 0, 1); PG8_SCHED; PG8_LDA(At, 0, 0); PG8_STAGE(PG8_SA(1, 1), a1 + hstepA, voffA);
;             PG8_WAIT_V(8); PG8_WAIT_L(0); PG8_BAR; PG8_MMA(0, 0, At, B0); PG8_MMA(0, 1, At, B1); PG8_BAR; PG8_SCHED;
.LBB0_345:
	s_add_u32 s6, s4, 0xfff80080
	s_addc_u32 s7, s5, -1
	s_add_i32 s73, 0, 0x10000
	s_cmp_eq_u32 s72, 28
	s_cselect_b32 s11, s23, s7
	s_cselect_b32 s10, s28, s6
	v_add_u32_e32 v144, s73, v139
	s_cselect_b32 s7, s21, s46
	s_cselect_b32 s6, s29, s33
	s_add_i32 s76, 0, 0x14000
	ds_read_b128 v[154:157], v144
	ds_read_b128 v[158:161], v144 offset:1024
	ds_read_b128 v[162:165], v144 offset:2048
	ds_read_b128 v[166:169], v144 offset:3072
	v_add_u32_e32 v144, s76, v139
	ds_read_b128 v[176:179], v144
	ds_read_b128 v[180:183], v144 offset:1024
	ds_read_b128 v[184:187], v144 offset:2048
	ds_read_b128 v[188:191], v144 offset:3072
	v_lshl_add_u64 v[144:145], s[4:5], 0, v[142:143]
	s_add_i32 m0, s35, 0xc000
	ds_read_b128 v[192:195], v174
	ds_read_b128 v[196:199], v174 offset:1024
	ds_read_b128 v[200:203], v174 offset:2048
	ds_read_b128 v[204:207], v174 offset:3072
	ds_read_b128 v[208:211], v174 offset:4096
	ds_read_b128 v[212:215], v174 offset:5120
	ds_read_b128 v[216:219], v174 offset:6144
	ds_read_b128 v[220:223], v174 offset:7168
	global_load_lds_dwordx4 v[144:145], off
	v_lshl_add_u64 v[144:145], s[4:5], 0, v[140:141]
	s_add_i32 m0, s35, 0xe000
	s_nop 0
	global_load_lds_dwordx4 v[144:145], off
	s_cmp_lg_u32 s72, -2
	s_cbranch_scc1 .Lpe_g1_w0n
	s_cmp_eq_u32 s3, 0
	s_cbranch_scc1 .Lpe_g1_w0n
	s_waitcnt vmcnt(16)
	s_branch .Lpe_g1_w0d

; #define PG8_STAGE(bufoff, gbase, voff) do { _Pragma("unroll") for (int _i = 0; _i < 2; ++_i) \
;         __builtin_amdgcn_global_load_lds((const unsigned*)((const char*)(gbase) + (voff)[_i]), (PG8_LAS unsigned*)(lds + (bufoff) + ldsw + _i * 8192), 16, 0, 0); } while (0)
; #define PG8_LDA(dst, b, h) do { _Pragma("unroll") for (int m = 0; m < 4; ++m) _Pragma("unroll") for (int k = 0; k < 2; ++k) dst[m][k] = *(const PG8_LAS bf16x8*)(lds + PG8_SA(b, h) + aoff + m * 2048 + k * 1024); } while (0)
; #define PG8_MMA(ai, bj, At, Bt) do { __builtin_amdgcn_s_setprio(1); _Pragma("unroll") for (int m = 0; m < 4; ++m) _Pragma("unroll") for (int n = 0; n < 2; ++n) _Pragma("unroll") for (int k = 0; k < 2; ++k) \
;         acc[ai][bj][m][n] = __builtin_amdgcn_mfma_f32_16x16x32_bf16(Bt[n][k], At[m][k], acc[ai][bj][m][n], 0, 0, 0); __builtin_amdgcn_s_setprio(0); } while (0)
; #define PG8_WAIT_V(n) asm volatile("s_waitcnt vmcnt(" #n ")" ::: "memory")
; #define PG8_WAIT_L(n) asm volatile("s_waitcnt lgkmcnt(" #n ")" ::: "memory")
; #define PG8_BAR __builtin_amdgcn_s_barrier()
; #define PG8_SCHED __builtin_amdgcn_sched_barrier(0)
; template <class Epi, class Sched, bool ALIGN_EPI = false, bool SP2 = true>
; __device__ __forceinline__ void gemm_phase(PG8_LAS unsigned char* lds, const Gemm g, const Sched& S, const Epi& E, int wave_s) {
;     ...
;             PG8_WAIT_V(8); PG8_WAIT_L(0); PG8_BAR; PG8_MMA(0, 0, At, B0); PG8_MMA(0, 1, At, B1); PG8_BAR; PG8_SCHED;
;             PG8_LDA(At, 0, 1); PG8_STAGE(PG8_SB(0, 0), b2, voffB); PG8_STAGE(PG8_SB(0, 1), b2 + hstepB, voffB); PG8_STAGE(PG8_SA(0, 0), a2, voffA);
.Lpe_g1_w0d:
	s_waitcnt lgkmcnt(0)
	s_barrier
	s_setprio 1
	v_mfma_f32_16x16x32_bf16 v[126:129], v[154:157], v[192:195], v[126:129]
	v_mfma_f32_16x16x32_bf16 v[122:125], v[162:165], v[192:195], v[122:125]
	v_mfma_f32_16x16x32_bf16 v[110:113], v[154:157], v[200:203], v[110:113]
	v_mfma_f32_16x16x32_bf16 v[106:109], v[162:165], v[200:203], v[106:109]
	v_mfma_f32_16x16x32_bf16 v[94:97], v[154:157], v[208:211], v[94:97]
	v_mfma_f32_16x16x32_bf16 v[90:93], v[162:165], v[208:211], v[90:93]
	v_mfma_f32_16x16x32_bf16 v[78:81], v[154:157], v[216:219], v[78:81]
	v_mfma_f32_16x16x32_bf16 v[74:77], v[162:165], v[216:219], v[74:77]
	v_mfma_f32_16x16x32_bf16 v[126:129], v[158:161], v[196:199], v[126:129]
	v_mfma_f32_16x16x32_bf16 v[122:125], v[166:169], v[196:199], v[122:125]
	v_mfma_f32_16x16x32_bf16 v[110:113], v[158:161], v[204:207], v[110:113]
	v_mfma_f32_16x16x32_bf16 v[106:109], v[166:169], v[204:207], v[106:109]
	v_mfma_f32_16x16x32_bf16 v[94:97], v[158:161], v[212:215], v[94:97]
	v_mfma_f32_16x16x32_bf16 v[90:93], v[166:169], v[212:215], v[90:93]
	v_mfma_f32_16x16x32_bf16 v[78:81], v[158:161], v[220:223], v[78:81]
	v_mfma_f32_16x16x32_bf16 v[74:77], v[166:169], v[220:223], v[74:77]
	v_mfma_f32_16x16x32_bf16 v[118:121], v[176:179], v[192:195], v[118:121]
	v_mfma_f32_16x16x32_bf16 v[114:117], v[184:187], v[192:195], v[114:117]
	v_mfma_f32_16x16x32_bf16 v[102:105], v[176:179], v[200:203], v[102:105]
	v_mfma_f32_16x16x32_bf16 v[98:101], v[184:187], v[200:203], v[98:101]
	v_mfma_f32_16x16x32_bf16 v[86:89], v[176:179], v[208:211], v[86:89]
	v_mfma_f32_16x16x32_bf16 v[82:85], v[184:187], v[208:211], v[82:85]
	v_mfma_f32_16x16x32_bf16 v[70:73], v[176:179], v[216:219], v[70:73]
	v_mfma_f32_16x16x32_bf16 v[66:69], v[184:187], v[216:219], v[66:69]
	v_mfma_f32_16x16x32_bf16 v[118:121], v[180:183], v[196:199], v[118:121]
	v_mfma_f32_16x16x32_bf16 v[114:117], v[188:191], v[196:199], v[114:117]
	v_mfma_f32_16x16x32_bf16 v[102:105], v[180:183], v[204:207], v[102:105]
	v_mfma_f32_16x16x32_bf16 v[98:101], v[188:191], v[204:207], v[98:101]
	v_mfma_f32_16x16x32_bf16 v[86:89], v[180:183], v[212:215], v[86:89]
	v_mfma_f32_16x16x32_bf16 v[82:85], v[188:191], v[212:215], v[82:85]
	v_mfma_f32_16x16x32_bf16 v[70:73], v[180:183], v[220:223], v[70:73]
	v_mfma_f32_16x16x32_bf16 v[66:69], v[188:191], v[220:223], v[66:69]
	s_setprio 0
	s_barrier
	s_add_i32 s73, s73, s34
	v_lshl_add_u64 v[144:145], s[6:7], 0, v[134:135]
	s_mov_b32 m0, s73
	ds_read_b128 v[192:195], v174 offset:16384
	ds_read_b128 v[196:199], v174 offset:17408
	ds_read_b128 v[200:203], v174 offset:18432
	ds_read_b128 v[204:207], v174 offset:19456
	ds_read_b128 v[208:211], v174 offset:20480
	ds_read_b128 v[212:215], v174 offset:21504
	ds_read_b128 v[216:219], v174 offset:22528
	ds_read_b128 v[220:223], v174 offset:23552
	global_load_lds_dwordx4 v[144:145], off
	s_add_i32 m0, s73, 0x2000
	s_add_u32 s74, s6, 0x80000
	v_lshl_add_u64 v[170:171], s[6:7], 0, v[130:131]
	s_addc_u32 s75, s7, 0
	s_add_i32 s73, s76, s34
	global_load_lds_dwordx4 v[170:171], off
	v_lshl_add_u64 v[224:225], s[74:75], 0, v[134:135]
	s_mov_b32 m0, s73
	v_lshl_add_u64 v[226:227], s[10:11], 0, v[132:133]
	global_load_lds_dwordx4 v[224:225], off
	v_lshl_add_u64 v[224:225], s[74:75], 0, v[130:131]
	s_add_i32 m0, s73, 0x2000
	s_nop 0
	global_load_lds_dwordx4 v[224:225], off
	v_lshl_add_u64 v[224:225], s[10:11], 0, v[136:137]
	s_mov_b32 m0, s35
	s_nop 0
	global_load_lds_dwordx4 v[224:225], off
	s_mov_b32 m0, s37
	s_nop 0
	global_load_lds_dwordx4 v[226:227], off
	s_cmp_lg_u32 s72, -2
	s_cbranch_scc1 .Lpe_g1_w1n
	s_cmp_eq_u32 s3, 0
	s_cbranch_scc1 .Lpe_g1_w1n
	s_waitcnt vmcnt(16)
	s_branch .Lpe_g1_w1d

; #define PG8_STAGE(bufoff, gbase, voff) do { _Pragma("unroll") for (int _i = 0; _i < 2; ++_i) \
;         __builtin_amdgcn_global_load_lds((const unsigned*)((const char*)(gbase) + (voff)[_i]), (PG8_LAS unsigned*)(lds + (bufoff) + ldsw + _i * 8192), 16, 0, 0); } while (0)
; #define PG8_LDA(dst, b, h) do { _Pragma("unroll") for (int m = 0; m < 4; ++m) _Pragma("unroll") for (int k = 0; k < 2; ++k) dst[m][k] = *(const PG8_LAS bf16x8*)(lds + PG8_SA(b, h) + aoff + m * 2048 + k * 1024); } while (0)
; #define PG8_LDB(dst, b, h) do { _Pragma("unroll") for (int n = 0; n < 2; ++n) _Pragma("unroll") for (int k = 0; k < 2; ++k) dst[n][k] = *(const PG8_LAS bf16x8*)(lds + PG8_SB(b, h) + boff + n * 2048 + k * 1024); } while (0)
; #define PG8_MMA(ai, bj, At, Bt) do { __builtin_amdgcn_s_setprio(1); _Pragma("unroll") for (int m = 0; m < 4; ++m) _Pragma("unroll") for (int n = 0; n < 2; ++n) _Pragma("unroll") for (int k = 0; k < 2; ++k) \
;         acc[ai][bj][m][n] = __builtin_amdgcn_mfma_f32_16x16x32_bf16(Bt[n][k], At[m][k], acc[ai][bj][m][n], 0, 0, 0); __builtin_amdgcn_s_setprio(0); } while (0)
; #define PG8_WAIT_V(n) asm volatile("s_waitcnt vmcnt(" #n ")" ::: "memory")
; #define PG8_WAIT_L(n) asm volatile("s_waitcnt lgkmcnt(" #n ")" ::: "memory")
; #define PG8_BAR __builtin_amdgcn_s_barrier()
; #define PG8_SCHED __builtin_amdgcn_sched_barrier(0)
; template <class Epi, class Sched, bool ALIGN_EPI = false, bool SP2 = true>
; __device__ __forceinline__ void gemm_phase(PG8_LAS unsigned char* lds, const Gemm g, const Sched& S, const Epi& E, int wave_s) {
;     ...
;             PG8_WAIT_V(8); PG8_WAIT_L(0); PG8_BAR; PG8_MMA(1, 0, At, B0); PG8_MMA(1, 1, At, B1); PG8_BAR; PG8_SCHED;
;             PG8_LDB(B0, 1, 0); PG8_LDB(B1, 1, 1); PG8_SCHED; PG8_LDA(At, 1, 0); PG8_STAGE(PG8_SA(0, 1), a2 + hstepA, voffA);
;             PG8_WAIT_V(8); PG8_WAIT_L(0); PG8_BAR; PG8_MMA(0, 0, At, B0); PG8_MMA(0, 1, At, B1); PG8_BAR; PG8_SCHED;
.Lpe_g1_w1d:
	s_waitcnt lgkmcnt(0)
	s_barrier
	s_setprio 1
	v_mfma_f32_16x16x32_bf16 v[62:65], v[154:157], v[192:195], v[62:65]
	v_mfma_f32_16x16x32_bf16 v[58:61], v[162:165], v[192:195], v[58:61]
	v_mfma_f32_16x16x32_bf16 v[46:49], v[154:157], v[200:203], v[46:49]
	v_mfma_f32_16x16x32_bf16 v[42:45], v[162:165], v[200:203], v[42:45]
	v_mfma_f32_16x16x32_bf16 v[30:33], v[154:157], v[208:211], v[30:33]
	v_mfma_f32_16x16x32_bf16 v[26:29], v[162:165], v[208:211], v[26:29]
	v_mfma_f32_16x16x32_bf16 v[14:17], v[154:157], v[216:219], v[14:17]
	v_mfma_f32_16x16x32_bf16 v[10:13], v[162:165], v[216:219], v[10:13]
	v_mfma_f32_16x16x32_bf16 v[62:65], v[158:161], v[196:199], v[62:65]
	v_mfma_f32_16x16x32_bf16 v[58:61], v[166:169], v[196:199], v[58:61]
	v_mfma_f32_16x16x32_bf16 v[46:49], v[158:161], v[204:207], v[46:49]
	v_mfma_f32_16x16x32_bf16 v[42:45], v[166:169], v[204:207], v[42:45]
	v_mfma_f32_16x16x32_bf16 v[30:33], v[158:161], v[212:215], v[30:33]
	v_mfma_f32_16x16x32_bf16 v[26:29], v[166:169], v[212:215], v[26:29]
	v_mfma_f32_16x16x32_bf16 v[14:17], v[158:161], v[220:223], v[14:17]
	v_mfma_f32_16x16x32_bf16 v[10:13], v[166:169], v[220:223], v[10:13]
	v_mfma_f32_16x16x32_bf16 v[54:57], v[176:179], v[192:195], v[54:57]
	v_mfma_f32_16x16x32_bf16 v[50:53], v[184:187], v[192:195], v[50:53]
	v_mfma_f32_16x16x32_bf16 v[38:41], v[176:179], v[200:203], v[38:41]
	v_mfma_f32_16x16x32_bf16 v[34:37], v[184:187], v[200:203], v[34:37]
	v_mfma_f32_16x16x32_bf16 v[22:25], v[176:179], v[208:211], v[22:25]
	v_mfma_f32_16x16x32_bf16 v[18:21], v[184:187], v[208:211], v[18:21]
	v_mfma_f32_16x16x32_bf16 v[6:9], v[176:179], v[216:219], v[6:9]
	v_mfma_f32_16x16x32_bf16 v[2:5], v[184:187], v[216:219], v[2:5]
	v_mfma_f32_16x16x32_bf16 v[54:57], v[180:183], v[196:199], v[54:57]
	v_mfma_f32_16x16x32_bf16 v[50:53], v[188:191], v[196:199], v[50:53]
	v_mfma_f32_16x16x32_bf16 v[38:41], v[180:183], v[204:207], v[38:41]
	v_mfma_f32_16x16x32_bf16 v[34:37], v[188:191], v[204:207], v[34:37]
	v_mfma_f32_16x16x32_bf16 v[22:25], v[180:183], v[212:215], v[22:25]
	v_mfma_f32_16x16x32_bf16 v[18:21], v[188:191], v[212:215], v[18:21]
	v_mfma_f32_16x16x32_bf16 v[6:9], v[180:183], v[220:223], v[6:9]
	v_mfma_f32_16x16x32_bf16 v[2:5], v[188:191], v[220:223], v[2:5]
	s_setprio 0
	s_barrier
	s_add_i32 s73, 0, 0x18000
	v_add_u32_e32 v146, s73, v139
	s_add_i32 s74, 0, 0x1c000
	ds_read_b128 v[154:157], v146
	ds_read_b128 v[158:161], v146 offset:1024
	ds_read_b128 v[162:165], v146 offset:2048
	ds_read_b128 v[166:169], v146 offset:3072
	v_add_u32_e32 v146, s74, v139
	ds_read_b128 v[176:179], v146
	ds_read_b128 v[180:183], v146 offset:1024
	ds_read_b128 v[184:187], v146 offset:2048
	ds_read_b128 v[188:191], v146 offset:3072
	s_add_u32 s10, s10, 0x80000
	s_addc_u32 s11, s11, 0
	s_mov_b32 m0, s38
	v_lshl_add_u64 v[228:229], s[10:11], 0, v[136:137]
	ds_read_b128 v[192:195], v174 offset:32768
	ds_read_b128 v[196:199], v174 offset:33792
	ds_read_b128 v[200:203], v174 offset:34816
	ds_read_b128 v[204:207], v174 offset:35840
	ds_read_b128 v[208:211], v174 offset:36864
	ds_read_b128 v[212:215], v174 offset:37888
	ds_read_b128 v[216:219], v174 offset:38912
	ds_read_b128 v[220:223], v174 offset:39936
	global_load_lds_dwordx4 v[228:229], off
	v_lshl_add_u64 v[228:229], s[10:11], 0, v[132:133]
	s_mov_b32 m0, s39
	s_nop 0
	global_load_lds_dwordx4 v[228:229], off
	s_waitcnt vmcnt(8)
	s_waitcnt lgkmcnt(0)
	s_barrier
	s_setprio 1
	v_mfma_f32_16x16x32_bf16 v[126:129], v[154:157], v[192:195], v[126:129]
	v_mfma_f32_16x16x32_bf16 v[122:125], v[162:165], v[192:195], v[122:125]
	v_mfma_f32_16x16x32_bf16 v[110:113], v[154:157], v[200:203], v[110:113]
	v_mfma_f32_16x16x32_bf16 v[106:109], v[162:165], v[200:203], v[106:109]
	v_mfma_f32_16x16x32_bf16 v[94:97], v[154:157], v[208:211], v[94:97]
	v_mfma_f32_16x16x32_bf16 v[90:93], v[162:165], v[208:211], v[90:93]
	v_mfma_f32_16x16x32_bf16 v[78:81], v[154:157], v[216:219], v[78:81]
	v_mfma_f32_16x16x32_bf16 v[74:77], v[162:165], v[216:219], v[74:77]
	v_mfma_f32_16x16x32_bf16 v[126:129], v[158:161], v[196:199], v[126:129]
	v_mfma_f32_16x16x32_bf16 v[122:125], v[166:169], v[196:199], v[122:125]
	v_mfma_f32_16x16x32_bf16 v[110:113], v[158:161], v[204:207], v[110:113]
	v_mfma_f32_16x16x32_bf16 v[106:109], v[166:169], v[204:207], v[106:109]
	v_mfma_f32_16x16x32_bf16 v[94:97], v[158:161], v[212:215], v[94:97]
	v_mfma_f32_16x16x32_bf16 v[90:93], v[166:169], v[212:215], v[90:93]
	v_mfma_f32_16x16x32_bf16 v[78:81], v[158:161], v[220:223], v[78:81]
	v_mfma_f32_16x16x32_bf16 v[74:77], v[166:169], v[220:223], v[74:77]
	v_mfma_f32_16x16x32_bf16 v[118:121], v[176:179], v[192:195], v[118:121]
	v_mfma_f32_16x16x32_bf16 v[114:117], v[184:187], v[192:195], v[114:117]
	v_mfma_f32_16x16x32_bf16 v[102:105], v[176:179], v[200:203], v[102:105]
	v_mfma_f32_16x16x32_bf16 v[98:101], v[184:187], v[200:203], v[98:101]
	v_mfma_f32_16x16x32_bf16 v[86:89], v[176:179], v[208:211], v[86:89]
	v_mfma_f32_16x16x32_bf16 v[82:85], v[184:187], v[208:211], v[82:85]
	v_mfma_f32_16x16x32_bf16 v[70:73], v[176:179], v[216:219], v[70:73]
	v_mfma_f32_16x16x32_bf16 v[66:69], v[184:187], v[216:219], v[66:69]
	v_mfma_f32_16x16x32_bf16 v[118:121], v[180:183], v[196:199], v[118:121]
	v_mfma_f32_16x16x32_bf16 v[114:117], v[188:191], v[196:199], v[114:117]
	v_mfma_f32_16x16x32_bf16 v[102:105], v[180:183], v[204:207], v[102:105]
	v_mfma_f32_16x16x32_bf16 v[98:101], v[188:191], v[204:207], v[98:101]
	v_mfma_f32_16x16x32_bf16 v[86:89], v[180:183], v[212:215], v[86:89]
	v_mfma_f32_16x16x32_bf16 v[82:85], v[188:191], v[212:215], v[82:85]
	v_mfma_f32_16x16x32_bf16 v[70:73], v[180:183], v[220:223], v[70:73]
	v_mfma_f32_16x16x32_bf16 v[66:69], v[188:191], v[220:223], v[66:69]
	s_setprio 0
	s_barrier
; #define PG8_STAGE(bufoff, gbase, voff) do { _Pragma("unroll") for (int _i = 0; _i < 2; ++_i) \
;         __builtin_amdgcn_global_load_lds((const unsigned*)((const char*)(gbase) + (voff)[_i]), (PG8_LAS unsigned*)(lds + (bufoff) + ldsw + _i * 8192), 16, 0, 0); } while (0)
; #define PG8_LDA(dst, b, h) do { _Pragma("unroll") for (int m = 0; m < 4; ++m) _Pragma("unroll") for (int k = 0; k < 2; ++k) dst[m][k] = *(const PG8_LAS bf16x8*)(lds + PG8_SA(b, h) + aoff + m * 2048 + k * 1024); } while (0)
; #define PG8_MMA(ai, bj, At, Bt) do { __builtin_amdgcn_s_setprio(1); _Pragma("unroll") for (int m = 0; m < 4; ++m) _Pragma("unroll") for (int n = 0; n < 2; ++n) _Pragma("unroll") for (int k = 0; k < 2; ++k) \
;         acc[ai][bj][m][n] = __builtin_amdgcn_mfma_f32_16x16x32_bf16(Bt[n][k], At[m][k], acc[ai][bj][m][n], 0, 0, 0); __builtin_amdgcn_s_setprio(0); } while (0)
; #define PG8_WAIT_V(n) asm volatile("s_waitcnt vmcnt(" #n ")" ::: "memory")
; #define PG8_WAIT_L(n) asm volatile("s_waitcnt lgkmcnt(" #n ")" ::: "memory")
; #define PG8_BAR __builtin_amdgcn_s_barrier()
; #define PG8_SCHED __builtin_amdgcn_sched_barrier(0)
; template <class Epi, class Sched, bool ALIGN_EPI = false, bool SP2 = true>
; __device__ __forceinline__ void gemm_phase(PG8_LAS unsigned char* lds, const Gemm g, const Sched& S, const Epi& E, int wave_s) {
;     ...
;             PG8_LDA(At, 1, 1); PG8_STAGE(PG8_SB(1, 0), b3, voffB); PG8_STAGE(PG8_SB(1, 1), b3 + hstepB, voffB); PG8_STAGE(PG8_SA(1, 0), a3, voffA);
;             PG8_WAIT_V(8); PG8_WAIT_L(0); PG8_BAR; PG8_MMA(1, 0, At, B0); PG8_MMA(1, 1, At, B1); PG8_BAR; PG8_SCHED;
;     ...
;         if constexpr (ALIGN_EPI) { if (wr == 0) PG8_BAR; }
	s_add_i32 s10, s73, s34
	v_lshl_add_u64 v[144:145], v[144:145], 0, s[78:79]
	s_mov_b32 m0, s10
	ds_read_b128 v[192:195], v174 offset:49152
	ds_read_b128 v[196:199], v174 offset:50176
	ds_read_b128 v[200:203], v174 offset:51200
	ds_read_b128 v[204:207], v174 offset:52224
	ds_read_b128 v[208:211], v174 offset:53248
	ds_read_b128 v[212:215], v174 offset:54272
	ds_read_b128 v[216:219], v174 offset:55296
	ds_read_b128 v[220:223], v174 offset:56320
	global_load_lds_dwordx4 v[144:145], off
	s_add_i32 m0, s10, 0x2000
	s_add_u32 s6, s6, 0x80080
	v_lshl_add_u64 v[144:145], v[170:171], 0, s[78:79]
	s_addc_u32 s7, s7, 0
	s_add_i32 s10, s74, s34
	global_load_lds_dwordx4 v[144:145], off
	v_lshl_add_u64 v[144:145], s[6:7], 0, v[134:135]
	s_mov_b32 m0, s10
	s_nop 0
	global_load_lds_dwordx4 v[144:145], off
	v_lshl_add_u64 v[144:145], s[6:7], 0, v[130:131]
	s_add_i32 m0, s10, 0x2000
	s_nop 0
	global_load_lds_dwordx4 v[144:145], off
	v_lshl_add_u64 v[144:145], v[224:225], 0, s[78:79]
	s_mov_b32 m0, s44
	s_nop 0
	global_load_lds_dwordx4 v[144:145], off
	v_lshl_add_u64 v[144:145], v[226:227], 0, s[78:79]
	s_mov_b32 m0, s45
	s_nop 0
	global_load_lds_dwordx4 v[144:145], off
	s_waitcnt vmcnt(8)
	s_waitcnt lgkmcnt(0)
	s_barrier
	s_setprio 1
	v_mfma_f32_16x16x32_bf16 v[62:65], v[154:157], v[192:195], v[62:65]
	v_mfma_f32_16x16x32_bf16 v[58:61], v[162:165], v[192:195], v[58:61]
	v_mfma_f32_16x16x32_bf16 v[46:49], v[154:157], v[200:203], v[46:49]
	v_mfma_f32_16x16x32_bf16 v[42:45], v[162:165], v[200:203], v[42:45]
	v_mfma_f32_16x16x32_bf16 v[30:33], v[154:157], v[208:211], v[30:33]
	v_mfma_f32_16x16x32_bf16 v[26:29], v[162:165], v[208:211], v[26:29]
	v_mfma_f32_16x16x32_bf16 v[14:17], v[154:157], v[216:219], v[14:17]
	v_mfma_f32_16x16x32_bf16 v[10:13], v[162:165], v[216:219], v[10:13]
	v_mfma_f32_16x16x32_bf16 v[62:65], v[158:161], v[196:199], v[62:65]
	v_mfma_f32_16x16x32_bf16 v[58:61], v[166:169], v[196:199], v[58:61]
	v_mfma_f32_16x16x32_bf16 v[46:49], v[158:161], v[204:207], v[46:49]
	v_mfma_f32_16x16x32_bf16 v[42:45], v[166:169], v[204:207], v[42:45]
	v_mfma_f32_16x16x32_bf16 v[30:33], v[158:161], v[212:215], v[30:33]
	v_mfma_f32_16x16x32_bf16 v[26:29], v[166:169], v[212:215], v[26:29]
	v_mfma_f32_16x16x32_bf16 v[14:17], v[158:161], v[220:223], v[14:17]
	v_mfma_f32_16x16x32_bf16 v[10:13], v[166:169], v[220:223], v[10:13]
	v_mfma_f32_16x16x32_bf16 v[54:57], v[176:179], v[192:195], v[54:57]
	v_mfma_f32_16x16x32_bf16 v[50:53], v[184:187], v[192:195], v[50:53]
	v_mfma_f32_16x16x32_bf16 v[38:41], v[176:179], v[200:203], v[38:41]
	v_mfma_f32_16x16x32_bf16 v[34:37], v[184:187], v[200:203], v[34:37]
	v_mfma_f32_16x16x32_bf16 v[22:25], v[176:179], v[208:211], v[22:25]
	v_mfma_f32_16x16x32_bf16 v[18:21], v[184:187], v[208:211], v[18:21]
	v_mfma_f32_16x16x32_bf16 v[6:9], v[176:179], v[216:219], v[6:9]
	v_mfma_f32_16x16x32_bf16 v[2:5], v[184:187], v[216:219], v[2:5]
	v_mfma_f32_16x16x32_bf16 v[54:57], v[180:183], v[196:199], v[54:57]
	v_mfma_f32_16x16x32_bf16 v[50:53], v[188:191], v[196:199], v[50:53]
	v_mfma_f32_16x16x32_bf16 v[38:41], v[180:183], v[204:207], v[38:41]
	v_mfma_f32_16x16x32_bf16 v[34:37], v[188:191], v[204:207], v[34:37]
	v_mfma_f32_16x16x32_bf16 v[22:25], v[180:183], v[212:215], v[22:25]
	v_mfma_f32_16x16x32_bf16 v[18:21], v[188:191], v[212:215], v[18:21]
	v_mfma_f32_16x16x32_bf16 v[6:9], v[180:183], v[220:223], v[6:9]
	v_mfma_f32_16x16x32_bf16 v[2:5], v[188:191], v[220:223], v[2:5]
	s_setprio 0
	s_barrier
	s_add_i32 s72, s72, 2
	s_add_u32 s33, s33, 0x100
	s_addc_u32 s46, s46, 0
	s_add_u32 s4, s4, 0x100
	s_addc_u32 s5, s5, 0
	s_cmp_gt_u32 s72, 29
	s_cbranch_scc0 .LBB0_345
	s_and_b64 vcc, exec, s[18:19]
	s_cbranch_vccz .LBB0_348
	s_barrier

; #define PG8_STAGE(bufoff, gbase, voff) do { _Pragma("unroll") for (int _i = 0; _i < 2; ++_i) \
;         __builtin_amdgcn_global_load_lds((const unsigned*)((const char*)(gbase) + (voff)[_i]), (PG8_LAS unsigned*)(lds + (bufoff) + ldsw + _i * 8192), 16, 0, 0); } while (0)
; #define PG8_LDA(dst, b, h) do { _Pragma("unroll") for (int m = 0; m < 4; ++m) _Pragma("unroll") for (int k = 0; k < 2; ++k) dst[m][k] = *(const PG8_LAS bf16x8*)(lds + PG8_SA(b, h) + aoff + m * 2048 + k * 1024); } while (0)
; #define PG8_LDB(dst, b, h) do { _Pragma("unroll") for (int n = 0; n < 2; ++n) _Pragma("unroll") for (int k = 0; k < 2; ++k) dst[n][k] = *(const PG8_LAS bf16x8*)(lds + PG8_SB(b, h) + boff + n * 2048 + k * 1024); } while (0)
; #define PG8_MMA(ai, bj, At, Bt) do { __builtin_amdgcn_s_setprio(1); _Pragma("unroll") for (int m = 0; m < 4; ++m) _Pragma("unroll") for (int n = 0; n < 2; ++n) _Pragma("unroll") for (int k = 0; k < 2; ++k) \
;         acc[ai][bj][m][n] = __builtin_amdgcn_mfma_f32_16x16x32_bf16(Bt[n][k], At[m][k], acc[ai][bj][m][n], 0, 0, 0); __builtin_amdgcn_s_setprio(0); } while (0)
; #define PG8_WAIT_V(n) asm volatile("s_waitcnt vmcnt(" #n ")" ::: "memory")
; #define PG8_WAIT_L(n) asm volatile("s_waitcnt lgkmcnt(" #n ")" ::: "memory")
; #define PG8_BAR __builtin_amdgcn_s_barrier()
; #define PG8_SCHED __builtin_amdgcn_sched_barrier(0)
; template <class Epi, class Sched, bool ALIGN_EPI = false, bool SP2 = true>
; __device__ __forceinline__ void gemm_phase(PG8_LAS unsigned char* lds, const Gemm g, const Sched& S, const Epi& E, int wave_s) {
;     ...
;             PG8_LDB(B0, 0, 0); PG8_LDB(B1, 0, 1); PG8_SCHED; PG8_LDA(At, 0, 0); PG8_STAGE(PG8_SA(1, 1), a1 + hstepA, voffA);
;             PG8_WAIT_V(8); PG8_WAIT_L(0); PG8_BAR; PG8_MMA(0, 0, At, B0); PG8_MMA(0, 1, At, B1); PG8_BAR; PG8_SCHED;
.LBB0_608:
	s_add_u32 s6, s24, 0x100
	s_addc_u32 s7, s25, 0
	s_add_i32 s75, 0, 0x10000
	s_cmp_eq_u32 s74, 28
	s_cselect_b32 s29, s21, s7
	s_cselect_b32 s28, s20, s6
	v_add_u32_e32 v146, s75, v170
	s_cselect_b32 s27, s19, s73
	s_cselect_b32 s26, s33, s72
	s_add_i32 s76, 0, 0x14000
	ds_read_b128 v[130:133], v146
	ds_read_b128 v[134:137], v146 offset:1024
	ds_read_b128 v[158:161], v146 offset:2048
	ds_read_b128 v[162:165], v146 offset:3072
	v_add_u32_e32 v146, s76, v170
	ds_read_b128 v[166:169], v146
	ds_read_b128 v[176:179], v146 offset:1024
	ds_read_b128 v[180:183], v146 offset:2048
	ds_read_b128 v[184:187], v146 offset:3072
	v_lshl_add_u64 v[146:147], s[24:25], 0, v[156:157]
	s_add_i32 m0, s35, 0xc000
	ds_read_b128 v[188:191], v174
	ds_read_b128 v[192:195], v174 offset:1024
	ds_read_b128 v[196:199], v174 offset:2048
	ds_read_b128 v[200:203], v174 offset:3072
	ds_read_b128 v[204:207], v174 offset:4096
	ds_read_b128 v[208:211], v174 offset:5120
	ds_read_b128 v[212:215], v174 offset:6144
	ds_read_b128 v[216:219], v174 offset:7168
	global_load_lds_dwordx4 v[146:147], off
	v_lshl_add_u64 v[146:147], s[24:25], 0, v[154:155]
	s_add_i32 m0, s35, 0xe000
	s_nop 0
	global_load_lds_dwordx4 v[146:147], off
	s_cmp_lg_u32 s74, -2
	s_cbranch_scc1 .Lpe_g3_w0n
	s_cmp_eq_u32 s1, 0
	s_cbranch_scc1 .Lpe_g3_w0n
	s_waitcnt vmcnt(16)
	s_branch .Lpe_g3_w0d

; #define PG8_STAGE(bufoff, gbase, voff) do { _Pragma("unroll") for (int _i = 0; _i < 2; ++_i) \
;         __builtin_amdgcn_global_load_lds((const unsigned*)((const char*)(gbase) + (voff)[_i]), (PG8_LAS unsigned*)(lds + (bufoff) + ldsw + _i * 8192), 16, 0, 0); } while (0)
; #define PG8_LDA(dst, b, h) do { _Pragma("unroll") for (int m = 0; m < 4; ++m) _Pragma("unroll") for (int k = 0; k < 2; ++k) dst[m][k] = *(const PG8_LAS bf16x8*)(lds + PG8_SA(b, h) + aoff + m * 2048 + k * 1024); } while (0)
; #define PG8_MMA(ai, bj, At, Bt) do { __builtin_amdgcn_s_setprio(1); _Pragma("unroll") for (int m = 0; m < 4; ++m) _Pragma("unroll") for (int n = 0; n < 2; ++n) _Pragma("unroll") for (int k = 0; k < 2; ++k) \
;         acc[ai][bj][m][n] = __builtin_amdgcn_mfma_f32_16x16x32_bf16(Bt[n][k], At[m][k], acc[ai][bj][m][n], 0, 0, 0); __builtin_amdgcn_s_setprio(0); } while (0)
; #define PG8_WAIT_V(n) asm volatile("s_waitcnt vmcnt(" #n ")" ::: "memory")
; #define PG8_WAIT_L(n) asm volatile("s_waitcnt lgkmcnt(" #n ")" ::: "memory")
; #define PG8_BAR __builtin_amdgcn_s_barrier()
; #define PG8_SCHED __builtin_amdgcn_sched_barrier(0)
; template <class Epi, class Sched, bool ALIGN_EPI = false, bool SP2 = true>
; __device__ __forceinline__ void gemm_phase(PG8_LAS unsigned char* lds, const Gemm g, const Sched& S, const Epi& E, int wave_s) {
;     ...
;             PG8_WAIT_V(8); PG8_WAIT_L(0); PG8_BAR; PG8_MMA(0, 0, At, B0); PG8_MMA(0, 1, At, B1); PG8_BAR; PG8_SCHED;
;             PG8_LDA(At, 0, 1); PG8_STAGE(PG8_SB(0, 0), b2, voffB); PG8_STAGE(PG8_SB(0, 1), b2 + hstepB, voffB); PG8_STAGE(PG8_SA(0, 0), a2, voffA);
.Lpe_g3_w0d:
	s_waitcnt lgkmcnt(0)
	s_barrier
	s_setprio 1
	v_mfma_f32_16x16x32_bf16 v[126:129], v[130:133], v[188:191], v[126:129]
	v_mfma_f32_16x16x32_bf16 v[122:125], v[158:161], v[188:191], v[122:125]
	v_mfma_f32_16x16x32_bf16 v[110:113], v[130:133], v[196:199], v[110:113]
	v_mfma_f32_16x16x32_bf16 v[106:109], v[158:161], v[196:199], v[106:109]
	v_mfma_f32_16x16x32_bf16 v[94:97], v[130:133], v[204:207], v[94:97]
	v_mfma_f32_16x16x32_bf16 v[90:93], v[158:161], v[204:207], v[90:93]
	v_mfma_f32_16x16x32_bf16 v[78:81], v[130:133], v[212:215], v[78:81]
	v_mfma_f32_16x16x32_bf16 v[74:77], v[158:161], v[212:215], v[74:77]
	v_mfma_f32_16x16x32_bf16 v[126:129], v[134:137], v[192:195], v[126:129]
	v_mfma_f32_16x16x32_bf16 v[122:125], v[162:165], v[192:195], v[122:125]
	v_mfma_f32_16x16x32_bf16 v[110:113], v[134:137], v[200:203], v[110:113]
	v_mfma_f32_16x16x32_bf16 v[106:109], v[162:165], v[200:203], v[106:109]
	v_mfma_f32_16x16x32_bf16 v[94:97], v[134:137], v[208:211], v[94:97]
	v_mfma_f32_16x16x32_bf16 v[90:93], v[162:165], v[208:211], v[90:93]
	v_mfma_f32_16x16x32_bf16 v[78:81], v[134:137], v[216:219], v[78:81]
	v_mfma_f32_16x16x32_bf16 v[74:77], v[162:165], v[216:219], v[74:77]
	v_mfma_f32_16x16x32_bf16 v[118:121], v[166:169], v[188:191], v[118:121]
	v_mfma_f32_16x16x32_bf16 v[114:117], v[180:183], v[188:191], v[114:117]
	v_mfma_f32_16x16x32_bf16 v[102:105], v[166:169], v[196:199], v[102:105]
	v_mfma_f32_16x16x32_bf16 v[98:101], v[180:183], v[196:199], v[98:101]
	v_mfma_f32_16x16x32_bf16 v[86:89], v[166:169], v[204:207], v[86:89]
	v_mfma_f32_16x16x32_bf16 v[82:85], v[180:183], v[204:207], v[82:85]
	v_mfma_f32_16x16x32_bf16 v[70:73], v[166:169], v[212:215], v[70:73]
	v_mfma_f32_16x16x32_bf16 v[66:69], v[180:183], v[212:215], v[66:69]
	v_mfma_f32_16x16x32_bf16 v[118:121], v[176:179], v[192:195], v[118:121]
	v_mfma_f32_16x16x32_bf16 v[114:117], v[184:187], v[192:195], v[114:117]
	v_mfma_f32_16x16x32_bf16 v[102:105], v[176:179], v[200:203], v[102:105]
	v_mfma_f32_16x16x32_bf16 v[98:101], v[184:187], v[200:203], v[98:101]
	v_mfma_f32_16x16x32_bf16 v[86:89], v[176:179], v[208:211], v[86:89]
	v_mfma_f32_16x16x32_bf16 v[82:85], v[184:187], v[208:211], v[82:85]
	v_mfma_f32_16x16x32_bf16 v[70:73], v[176:179], v[216:219], v[70:73]
	v_mfma_f32_16x16x32_bf16 v[66:69], v[184:187], v[216:219], v[66:69]
	s_setprio 0
	s_barrier
	s_add_i32 s24, s75, s34
	v_lshl_add_u64 v[146:147], s[26:27], 0, v[142:143]
	s_mov_b32 m0, s24
	ds_read_b128 v[188:191], v174 offset:16384
	ds_read_b128 v[192:195], v174 offset:17408
	ds_read_b128 v[196:199], v174 offset:18432
	ds_read_b128 v[200:203], v174 offset:19456
	ds_read_b128 v[204:207], v174 offset:20480
	ds_read_b128 v[208:211], v174 offset:21504
	ds_read_b128 v[212:215], v174 offset:22528
	ds_read_b128 v[216:219], v174 offset:23552
	global_load_lds_dwordx4 v[146:147], off
	s_add_i32 m0, s24, 0x2000
	s_add_u32 s24, s26, 0x80000
	v_lshl_add_u64 v[220:221], s[26:27], 0, v[138:139]
	s_addc_u32 s25, s27, 0
	s_add_i32 s75, s76, s34
	global_load_lds_dwordx4 v[220:221], off
	v_lshl_add_u64 v[222:223], s[24:25], 0, v[142:143]
	s_mov_b32 m0, s75
	v_lshl_add_u64 v[224:225], s[28:29], 0, v[140:141]
	global_load_lds_dwordx4 v[222:223], off
	v_lshl_add_u64 v[222:223], s[24:25], 0, v[138:139]
	s_add_i32 m0, s75, 0x2000
	s_nop 0
	global_load_lds_dwordx4 v[222:223], off
	v_lshl_add_u64 v[222:223], s[28:29], 0, v[144:145]
	s_mov_b32 m0, s35
	s_nop 0
	global_load_lds_dwordx4 v[222:223], off
	s_mov_b32 m0, s37
	s_nop 0
	global_load_lds_dwordx4 v[224:225], off
	s_cmp_lt_i32 s74, 0
	s_cbranch_scc1 .Lrf_join
	s_cmp_eq_u32 s92, 0
	s_cbranch_scc1 .Lrf_tree
	v_lshlrev_b32_e32 v240, 16, v228
	v_and_b32_e32 v241, 0xffff0000, v228
	v_lshlrev_b32_e32 v242, 16, v229
	v_and_b32_e32 v243, 0xffff0000, v229
	v_lshlrev_b32_e32 v244, 16, v230
	v_and_b32_e32 v245, 0xffff0000, v230
	v_lshlrev_b32_e32 v246, 16, v231
	v_and_b32_e32 v247, 0xffff0000, v231

; #define PG8_MMA(ai, bj, At, Bt) do { __builtin_amdgcn_s_setprio(1); _Pragma("unroll") for (int m = 0; m < 4; ++m) _Pragma("unroll") for (int n = 0; n < 2; ++n) _Pragma("unroll") for (int k = 0; k < 2; ++k) \
;         acc[ai][bj][m][n] = __builtin_amdgcn_mfma_f32_16x16x32_bf16(Bt[n][k], At[m][k], acc[ai][bj][m][n], 0, 0, 0); __builtin_amdgcn_s_setprio(0); } while (0)
; #define PG8_WAIT_V(n) asm volatile("s_waitcnt vmcnt(" #n ")" ::: "memory")
; #define PG8_WAIT_L(n) asm volatile("s_waitcnt lgkmcnt(" #n ")" ::: "memory")
; #define PG8_BAR __builtin_amdgcn_s_barrier()
; #define PG8_SCHED __builtin_amdgcn_sched_barrier(0)
; template <class Epi, class Sched, bool ALIGN_EPI = false, bool SP2 = true>
; __device__ __forceinline__ void gemm_phase(PG8_LAS unsigned char* lds, const Gemm g, const Sched& S, const Epi& E, int wave_s) {
;     ...
;             PG8_WAIT_V(8); PG8_WAIT_L(0); PG8_BAR; PG8_MMA(1, 0, At, B0); PG8_MMA(1, 1, At, B1); PG8_BAR; PG8_SCHED;
.Lrf_join:
	s_cmp_lg_u32 s74, -2
	s_cbranch_scc1 .Lpe_g3_w1n
	s_cmp_eq_u32 s1, 0
	s_cbranch_scc1 .Lpe_g3_w1n
	s_waitcnt vmcnt(16)
	s_branch .Lpe_g3_w1d

; #define GAS __attribute__((address_space(1)))
; __device__ __forceinline__ float bf_lo(unsigned w) { return __uint_as_float(w << 16); }
; __device__ __forceinline__ float bf_hi(unsigned w) { return __uint_as_float(w & 0xffff0000u); }
; #define PG8_MMA(ai, bj, At, Bt) do { __builtin_amdgcn_s_setprio(1); _Pragma("unroll") for (int m = 0; m < 4; ++m) _Pragma("unroll") for (int n = 0; n < 2; ++n) _Pragma("unroll") for (int k = 0; k < 2; ++k) \
;         acc[ai][bj][m][n] = __builtin_amdgcn_mfma_f32_16x16x32_bf16(Bt[n][k], At[m][k], acc[ai][bj][m][n], 0, 0, 0); __builtin_amdgcn_s_setprio(0); } while (0)
; #define PG8_WAIT_V(n) asm volatile("s_waitcnt vmcnt(" #n ")" ::: "memory")
; #define PG8_WAIT_L(n) asm volatile("s_waitcnt lgkmcnt(" #n ")" ::: "memory")
; #define PG8_BAR __builtin_amdgcn_s_barrier()
; #define PG8_SCHED __builtin_amdgcn_sched_barrier(0)
;     __device__ __forceinline__ void operator()(const f32x4 (&acc)[2][2][4][2], const Unit& u, int wr, int wc, int fr, int fq, const PG8_LAS float* tab) const {
;     ...
;                     if (mode == 0) { a0 = *(const GAS f32x4*)(xo + col0); a1 = *(const GAS f32x4*)(xo + col0 + 4); }
;                     else { const u32x4 w = *(const GAS u32x4*)(xr + col0);
;                         a0 = (f32x4){bf_lo(w.x), bf_hi(w.x), bf_lo(w.y), bf_hi(w.y)}; a1 = (f32x4){bf_lo(w.z), bf_hi(w.z), bf_lo(w.w), bf_hi(w.w)}; }
; template <class Epi, class Sched, bool ALIGN_EPI = false, bool SP2 = true>
; __device__ __forceinline__ void gemm_phase(PG8_LAS unsigned char* lds, const Gemm g, const Sched& S, const Epi& E, int wave_s) {
;     ...
;             PG8_WAIT_V(8); PG8_WAIT_L(0); PG8_BAR; PG8_MMA(1, 0, At, B0); PG8_MMA(1, 1, At, B1); PG8_BAR; PG8_SCHED;
.Lpe_g3_w1d:
	s_waitcnt lgkmcnt(0)
	s_barrier
	s_setprio 1
	v_mfma_f32_16x16x32_bf16 v[62:65], v[130:133], v[188:191], v[62:65]
	v_mfma_f32_16x16x32_bf16 v[58:61], v[158:161], v[188:191], v[58:61]
	v_mfma_f32_16x16x32_bf16 v[46:49], v[130:133], v[196:199], v[46:49]
	v_mfma_f32_16x16x32_bf16 v[42:45], v[158:161], v[196:199], v[42:45]
	v_mfma_f32_16x16x32_bf16 v[30:33], v[130:133], v[204:207], v[30:33]
	v_mfma_f32_16x16x32_bf16 v[26:29], v[158:161], v[204:207], v[26:29]
	v_mfma_f32_16x16x32_bf16 v[14:17], v[130:133], v[212:215], v[14:17]
	v_mfma_f32_16x16x32_bf16 v[10:13], v[158:161], v[212:215], v[10:13]
	v_mfma_f32_16x16x32_bf16 v[62:65], v[134:137], v[192:195], v[62:65]
	v_mfma_f32_16x16x32_bf16 v[58:61], v[162:165], v[192:195], v[58:61]
	v_mfma_f32_16x16x32_bf16 v[46:49], v[134:137], v[200:203], v[46:49]
	v_mfma_f32_16x16x32_bf16 v[42:45], v[162:165], v[200:203], v[42:45]
	v_mfma_f32_16x16x32_bf16 v[30:33], v[134:137], v[208:211], v[30:33]
	v_mfma_f32_16x16x32_bf16 v[26:29], v[162:165], v[208:211], v[26:29]
	v_mfma_f32_16x16x32_bf16 v[14:17], v[134:137], v[216:219], v[14:17]
	v_mfma_f32_16x16x32_bf16 v[10:13], v[162:165], v[216:219], v[10:13]
	v_mfma_f32_16x16x32_bf16 v[54:57], v[166:169], v[188:191], v[54:57]
	v_mfma_f32_16x16x32_bf16 v[50:53], v[180:183], v[188:191], v[50:53]
	v_mfma_f32_16x16x32_bf16 v[38:41], v[166:169], v[196:199], v[38:41]
	v_mfma_f32_16x16x32_bf16 v[34:37], v[180:183], v[196:199], v[34:37]
	v_mfma_f32_16x16x32_bf16 v[22:25], v[166:169], v[204:207], v[22:25]
	v_mfma_f32_16x16x32_bf16 v[18:21], v[180:183], v[204:207], v[18:21]
	v_mfma_f32_16x16x32_bf16 v[6:9], v[166:169], v[212:215], v[6:9]
	v_mfma_f32_16x16x32_bf16 v[2:5], v[180:183], v[212:215], v[2:5]
	v_mfma_f32_16x16x32_bf16 v[54:57], v[176:179], v[192:195], v[54:57]
	v_mfma_f32_16x16x32_bf16 v[50:53], v[184:187], v[192:195], v[50:53]
	v_mfma_f32_16x16x32_bf16 v[38:41], v[176:179], v[200:203], v[38:41]
	v_mfma_f32_16x16x32_bf16 v[34:37], v[184:187], v[200:203], v[34:37]
	v_mfma_f32_16x16x32_bf16 v[22:25], v[176:179], v[208:211], v[22:25]
	v_mfma_f32_16x16x32_bf16 v[18:21], v[184:187], v[208:211], v[18:21]
	v_mfma_f32_16x16x32_bf16 v[6:9], v[176:179], v[216:219], v[6:9]
	v_mfma_f32_16x16x32_bf16 v[2:5], v[184:187], v[216:219], v[2:5]
	s_setprio 0
	s_barrier
	s_add_i32 s77, s74, 2
	s_lshr_b32 s32, s77, 4
	s_lshl_b32 s32, s32, 20
	s_bfe_u32 s100, s77, 0x20002
	s_lshl_b32 s100, s100, 17
	s_or_b32 s32, s32, s100
	s_and_b32 s100, s77, 2
	s_lshl_b32 s100, s100, 8
	s_or_b32 s32, s32, s100
	s_and_b32 s100, s92, 1
	s_lshr_b32 s32, s32, s100
	s_add_u32 s100, s94, s32
	s_addc_u32 s101, s95, 0
	s_cmp_eq_u32 s92, 0
	s_cbranch_scc0 .Lrf_ld_m1
	global_load_dwordx4 v[240:243], v250, s[100:101]
	global_load_dwordx4 v[244:247], v250, s[100:101] offset:16
	s_branch .Lrf_ld_done
